# base16 + F unit switch: first two phase waits after an epilogue count the epilogue stores (vmcnt(40)) instead of draining them
# baseline (speedup 1.0000x reference)
; __global__ void __launch_bounds__(NTHREADS, 2) fwd_kernel(Args args) {
;     ...
;         if (EN(4) && INP(pb + 5)) { MKW();
;             pg8::Order<MapP> S; S.init(nMr, 16, w.G, c); S.map = MapP{(const char*)(ws + WS_OUTS), (const char*)(ws + WS_WBR)};
;             EpiP E{(bf16*)(ws + WS_P)};
;             pg8::gemm_phase<EpiP, pg8::Order<MapP>>(lds, pg8::Gemm{256, 1024, 256}, S, E);
.LBB0_1771:
	s_mov_b32 s32, 0
	s_cmp_le_i32 s48, s16
	s_cselect_b64 s[0:1], -1, 0
	s_cmp_lt_i32 s16, s49
	s_cselect_b64 s[2:3], -1, 0
	s_and_b64 s[2:3], s[0:1], s[2:3]
	s_mov_b64 s[0:1], -1
	s_and_b64 vcc, exec, s[2:3]
	s_cbranch_vccnz .LBB0_1773
	v_readlane_b32 s0, v255, 8
	s_add_i32 s16, s0, 8
	s_mov_b64 s[0:1], 0

; #define PG8_STAGE(bufoff, gbase, voff) do { _Pragma("unroll") for (int _i = 0; _i < 2; ++_i) \
;         __builtin_amdgcn_global_load_lds((const unsigned*)((const char*)(gbase) + (voff)[_i]), (LAS unsigned*)(lds + (bufoff) + ldsw + _i * 8192), 16, 0, 0); } while (0)
; #define PG8_WAIT_V(n) asm volatile("s_waitcnt vmcnt(" #n ")" ::: "memory")
; #define PG8_WAIT_L(n) asm volatile("s_waitcnt lgkmcnt(" #n ")" ::: "memory")
; #define PG8_BAR __builtin_amdgcn_s_barrier()
; #define PG8_SCHED __builtin_amdgcn_sched_barrier(0)
;     ...
;             PG8_LDB(B0, 0, 0); PG8_LDB(B1, 0, 1); PG8_SCHED; PG8_LDA(At, 0, 0); PG8_STAGE(PG8_SA(1, 1), a1 + hstepA, gc1);
;             PG8_WAIT_V(8); PG8_WAIT_L(0); PG8_BAR; PG8_MMA(0, 0, At, B0); PG8_MMA(0, 1, At, B1); PG8_BAR; PG8_SCHED;
;             PG8_LDA(At, 0, 1); PG8_STAGE(PG8_SB(0, 0), b2, voffB); PG8_STAGE(PG8_SB(0, 1), b2 + hstepB, voffB); PG8_STAGE(PG8_SA(0, 0), a2, s0);
;             PG8_WAIT_V(8); PG8_WAIT_L(0); PG8_BAR; PG8_MMA(1, 0, At, B0); PG8_MMA(1, 1, At, B1); PG8_BAR; PG8_SCHED;
.LBB0_1783:
	s_add_u32 s11, s42, s16
	s_addc_u32 s22, s43, s17
	s_add_u32 s28, s11, 0x100
	s_addc_u32 s29, s22, 0
	s_and_b64 s[24:25], s[14:15], exec
	s_cselect_b32 s25, s13, s29
	s_cselect_b32 s24, s12, s28
	s_add_u32 s16, s44, s16
	s_addc_u32 s17, s45, s17
	s_add_u32 s16, s16, 0x100
	s_addc_u32 s17, s17, 0
	s_add_i32 s67, 0, 0x10000
	s_and_b64 s[14:15], s[14:15], exec
	s_cselect_b32 s29, s37, s17
	s_cselect_b32 s28, s36, s16
	s_add_i32 s15, 0, 0x14000
	s_add_u32 s34, s11, 0x40080
	s_addc_u32 s35, s22, 0
	s_add_i32 s66, s67, s47
	s_add_i32 m0, s51, 0xc000
	s_add_i32 s22, s51, 0xe000
	s_add_i32 s63, s66, 0x2000
	s_add_u32 s30, s28, 0x10000
	v_add_u32_e32 v162, s67, v148
	v_add_u32_e32 v178, s15, v148
	s_addc_u32 s31, s29, 0
	s_add_i32 s65, s15, s47
	ds_read_b128 v[150:153], v162
	ds_read_b128 v[154:157], v162 offset:1024
	ds_read_b128 v[158:161], v162 offset:2048
	ds_read_b128 v[162:165], v162 offset:3072
	ds_read_b128 v[166:169], v178
	ds_read_b128 v[170:173], v178 offset:1024
	ds_read_b128 v[174:177], v178 offset:2048
	ds_read_b128 v[178:181], v178 offset:3072
	s_add_i32 s64, s65, 0x2000
	s_add_i32 s62, 0, 0x18000
	s_add_i32 s41, 0, 0x1c000
	s_add_u32 s16, s24, 0x40000
	s_addc_u32 s17, s25, 0
	s_add_i32 s33, s62, s47
	s_add_i32 s11, s33, 0x2000
	s_add_u32 s14, s28, 0x10080
	s_addc_u32 s15, s29, 0
	s_add_i32 s68, s41, s47
	s_add_i32 s67, s68, 0x2000
	v_lshl_add_u64 v[194:195], s[34:35], 0, v[138:139]
	ds_read_b128 v[182:185], v149
	ds_read_b128 v[186:189], v149 offset:1024
	ds_read_b128 v[190:193], v149 offset:2048
	ds_read_b128 v[200:203], v149 offset:3072
	ds_read_b128 v[204:207], v149 offset:4096
	ds_read_b128 v[208:211], v149 offset:5120
	ds_read_b128 v[212:215], v149 offset:6144
	ds_read_b128 v[216:219], v149 offset:7168
	global_load_lds_dwordx4 v[194:195], off
	v_lshl_add_u64 v[194:195], s[34:35], 0, v[134:135]
	s_mov_b32 m0, s22
	s_nop 0
	global_load_lds_dwordx4 v[194:195], off
	s_waitcnt vmcnt(40)
	s_cmp_lg_u32 s32, 0
	s_cbranch_scc1 .Lepirelax_F1
	s_waitcnt vmcnt(8)
.Lepirelax_F1:
	s_waitcnt lgkmcnt(0)
	s_barrier
	s_setprio 1
	s_waitcnt lgkmcnt(0)
	v_mfma_f32_16x16x32_bf16 v[128:131], v[150:153], v[182:185], v[128:131]
	v_mfma_f32_16x16x32_bf16 v[124:127], v[158:161], v[182:185], v[124:127]
	v_mfma_f32_16x16x32_bf16 v[116:119], v[150:153], v[190:193], v[116:119]
	v_mfma_f32_16x16x32_bf16 v[112:115], v[158:161], v[190:193], v[112:115]
	v_mfma_f32_16x16x32_bf16 v[104:107], v[150:153], v[204:207], v[104:107]
	v_mfma_f32_16x16x32_bf16 v[96:99], v[158:161], v[204:207], v[96:99]
	v_mfma_f32_16x16x32_bf16 v[88:91], v[150:153], v[212:215], v[88:91]
	v_mfma_f32_16x16x32_bf16 v[80:83], v[158:161], v[212:215], v[80:83]
	v_mfma_f32_16x16x32_bf16 v[128:131], v[154:157], v[186:189], v[128:131]
	v_mfma_f32_16x16x32_bf16 v[124:127], v[162:165], v[186:189], v[124:127]
	v_mfma_f32_16x16x32_bf16 v[116:119], v[154:157], v[200:203], v[116:119]
	v_mfma_f32_16x16x32_bf16 v[112:115], v[162:165], v[200:203], v[112:115]
	v_mfma_f32_16x16x32_bf16 v[104:107], v[154:157], v[208:211], v[104:107]
	v_mfma_f32_16x16x32_bf16 v[96:99], v[162:165], v[208:211], v[96:99]
	v_mfma_f32_16x16x32_bf16 v[88:91], v[154:157], v[216:219], v[88:91]
	v_mfma_f32_16x16x32_bf16 v[80:83], v[162:165], v[216:219], v[80:83]
	s_setprio 0
	s_setprio 1
	v_mfma_f32_16x16x32_bf16 v[120:123], v[166:169], v[182:185], v[120:123]
	v_mfma_f32_16x16x32_bf16 v[108:111], v[174:177], v[182:185], v[108:111]
	v_mfma_f32_16x16x32_bf16 v[100:103], v[166:169], v[190:193], v[100:103]
	v_mfma_f32_16x16x32_bf16 v[92:95], v[174:177], v[190:193], v[92:95]
	v_mfma_f32_16x16x32_bf16 v[84:87], v[166:169], v[204:207], v[84:87]
	v_mfma_f32_16x16x32_bf16 v[76:79], v[174:177], v[204:207], v[76:79]
	v_mfma_f32_16x16x32_bf16 v[72:75], v[166:169], v[212:215], v[72:75]
	v_mfma_f32_16x16x32_bf16 v[68:71], v[174:177], v[212:215], v[68:71]
	v_mfma_f32_16x16x32_bf16 v[120:123], v[170:173], v[186:189], v[120:123]
	v_mfma_f32_16x16x32_bf16 v[108:111], v[178:181], v[186:189], v[108:111]
	v_mfma_f32_16x16x32_bf16 v[100:103], v[170:173], v[200:203], v[100:103]
	v_mfma_f32_16x16x32_bf16 v[92:95], v[178:181], v[200:203], v[92:95]
	v_mfma_f32_16x16x32_bf16 v[84:87], v[170:173], v[208:211], v[84:87]
	v_mfma_f32_16x16x32_bf16 v[76:79], v[178:181], v[208:211], v[76:79]
	v_mfma_f32_16x16x32_bf16 v[72:75], v[170:173], v[216:219], v[72:75]
	v_mfma_f32_16x16x32_bf16 v[68:71], v[178:181], v[216:219], v[68:71]
	s_setprio 0
	s_barrier
	s_mov_b32 m0, s66
	v_lshl_add_u64 v[194:195], s[28:29], 0, v[136:137]
	ds_read_b128 v[182:185], v149 offset:16384
	ds_read_b128 v[186:189], v149 offset:17408
	ds_read_b128 v[190:193], v149 offset:18432
	ds_read_b128 v[200:203], v149 offset:19456
	ds_read_b128 v[204:207], v149 offset:20480
	ds_read_b128 v[208:211], v149 offset:21504
	ds_read_b128 v[212:215], v149 offset:22528
	ds_read_b128 v[216:219], v149 offset:23552
	global_load_lds_dwordx4 v[194:195], off
	v_lshl_add_u64 v[220:221], s[28:29], 0, v[132:133]
	s_mov_b32 m0, s63
	v_lshl_add_u64 v[222:223], s[30:31], 0, v[136:137]
	global_load_lds_dwordx4 v[220:221], off
	s_mov_b32 m0, s65
	v_lshl_add_u64 v[224:225], s[24:25], 0, v[134:135]
	global_load_lds_dwordx4 v[222:223], off
	v_lshl_add_u64 v[222:223], s[30:31], 0, v[132:133]
	s_mov_b32 m0, s64
	s_nop 0
	global_load_lds_dwordx4 v[222:223], off
	v_lshl_add_u64 v[222:223], s[24:25], 0, v[138:139]
	s_mov_b32 m0, s51
	s_nop 0
	global_load_lds_dwordx4 v[222:223], off
	s_mov_b32 m0, s52
	s_nop 0
	global_load_lds_dwordx4 v[224:225], off
	s_waitcnt vmcnt(40)
	s_cmp_lg_u32 s32, 0
	s_cbranch_scc1 .Lepirelax_F2
	s_waitcnt vmcnt(8)
; #define PG8_STAGE(bufoff, gbase, voff) do { _Pragma("unroll") for (int _i = 0; _i < 2; ++_i) \
;         __builtin_amdgcn_global_load_lds((const unsigned*)((const char*)(gbase) + (voff)[_i]), (LAS unsigned*)(lds + (bufoff) + ldsw + _i * 8192), 16, 0, 0); } while (0)
; #define PG8_WAIT_V(n) asm volatile("s_waitcnt vmcnt(" #n ")" ::: "memory")
; #define PG8_WAIT_L(n) asm volatile("s_waitcnt lgkmcnt(" #n ")" ::: "memory")
; #define PG8_BAR __builtin_amdgcn_s_barrier()
; #define PG8_SCHED __builtin_amdgcn_sched_barrier(0)
;     ...
;             PG8_WAIT_V(8); PG8_WAIT_L(0); PG8_BAR; PG8_MMA(1, 0, At, B0); PG8_MMA(1, 1, At, B1); PG8_BAR; PG8_SCHED;
;             PG8_LDB(B0, 1, 0); PG8_LDB(B1, 1, 1); PG8_SCHED; PG8_LDA(At, 1, 0); PG8_STAGE(PG8_SA(0, 1), a2 + hstepA, s1);
;             PG8_WAIT_V(8); PG8_WAIT_L(0); PG8_BAR; PG8_MMA(0, 0, At, B0); PG8_MMA(0, 1, At, B1); PG8_BAR; PG8_SCHED;
.Lepirelax_F2:
	s_mov_b32 s32, 0
	s_waitcnt lgkmcnt(0)
	s_barrier
	s_setprio 1
	s_waitcnt lgkmcnt(0)
	v_mfma_f32_16x16x32_bf16 v[64:67], v[150:153], v[182:185], v[64:67]
	v_mfma_f32_16x16x32_bf16 v[60:63], v[158:161], v[182:185], v[60:63]
	v_mfma_f32_16x16x32_bf16 v[46:49], v[150:153], v[190:193], v[46:49]
	v_mfma_f32_16x16x32_bf16 v[38:41], v[158:161], v[190:193], v[38:41]
	v_mfma_f32_16x16x32_bf16 v[22:25], v[150:153], v[204:207], v[22:25]
	v_mfma_f32_16x16x32_bf16 v[14:17], v[158:161], v[204:207], v[14:17]
	v_mfma_f32_16x16x32_bf16 v[6:9], v[150:153], v[212:215], v[6:9]
	v_mfma_f32_16x16x32_bf16 v[2:5], v[158:161], v[212:215], v[2:5]
	v_mfma_f32_16x16x32_bf16 v[64:67], v[154:157], v[186:189], v[64:67]
	v_mfma_f32_16x16x32_bf16 v[60:63], v[162:165], v[186:189], v[60:63]
	v_mfma_f32_16x16x32_bf16 v[46:49], v[154:157], v[200:203], v[46:49]
	v_mfma_f32_16x16x32_bf16 v[38:41], v[162:165], v[200:203], v[38:41]
	v_mfma_f32_16x16x32_bf16 v[22:25], v[154:157], v[208:211], v[22:25]
	v_mfma_f32_16x16x32_bf16 v[14:17], v[162:165], v[208:211], v[14:17]
	v_mfma_f32_16x16x32_bf16 v[6:9], v[154:157], v[216:219], v[6:9]
	v_mfma_f32_16x16x32_bf16 v[2:5], v[162:165], v[216:219], v[2:5]
	s_setprio 0
	s_setprio 1
	v_mfma_f32_16x16x32_bf16 v[52:55], v[166:169], v[182:185], v[52:55]
	v_mfma_f32_16x16x32_bf16 v[34:37], v[174:177], v[182:185], v[34:37]
	v_mfma_f32_16x16x32_bf16 v[18:21], v[166:169], v[190:193], v[18:21]
	v_mfma_f32_16x16x32_bf16 v[10:13], v[174:177], v[190:193], v[10:13]
	v_mfma_f32_16x16x32_bf16 v[56:59], v[166:169], v[204:207], v[56:59]
	v_mfma_f32_16x16x32_bf16 v[42:45], v[174:177], v[204:207], v[42:45]
	v_mfma_f32_16x16x32_bf16 v[30:33], v[166:169], v[212:215], v[30:33]
	v_mfma_f32_16x16x32_bf16 v[26:29], v[174:177], v[212:215], v[26:29]
	v_mfma_f32_16x16x32_bf16 v[52:55], v[170:173], v[186:189], v[52:55]
	v_mfma_f32_16x16x32_bf16 v[34:37], v[178:181], v[186:189], v[34:37]
	v_mfma_f32_16x16x32_bf16 v[18:21], v[170:173], v[200:203], v[18:21]
	v_mfma_f32_16x16x32_bf16 v[10:13], v[178:181], v[200:203], v[10:13]
	v_mfma_f32_16x16x32_bf16 v[56:59], v[170:173], v[208:211], v[56:59]
	v_mfma_f32_16x16x32_bf16 v[42:45], v[178:181], v[208:211], v[42:45]
	v_mfma_f32_16x16x32_bf16 v[30:33], v[170:173], v[216:219], v[30:33]
	v_mfma_f32_16x16x32_bf16 v[26:29], v[178:181], v[216:219], v[26:29]
	s_setprio 0
	s_barrier
	v_add_u32_e32 v162, s62, v148
	v_add_u32_e32 v178, s41, v148
	ds_read_b128 v[150:153], v162
	ds_read_b128 v[154:157], v162 offset:1024
	ds_read_b128 v[158:161], v162 offset:2048
	ds_read_b128 v[162:165], v162 offset:3072
	ds_read_b128 v[166:169], v178
	ds_read_b128 v[170:173], v178 offset:1024
	ds_read_b128 v[174:177], v178 offset:2048
	ds_read_b128 v[178:181], v178 offset:3072
	s_mov_b32 m0, s53
	v_lshl_add_u64 v[226:227], s[16:17], 0, v[138:139]
	ds_read_b128 v[182:185], v149 offset:32768
	ds_read_b128 v[186:189], v149 offset:33792
	ds_read_b128 v[190:193], v149 offset:34816
	ds_read_b128 v[200:203], v149 offset:35840
	ds_read_b128 v[204:207], v149 offset:36864
	ds_read_b128 v[208:211], v149 offset:37888
	ds_read_b128 v[212:215], v149 offset:38912
	ds_read_b128 v[216:219], v149 offset:39936
	global_load_lds_dwordx4 v[226:227], off
	v_lshl_add_u64 v[226:227], s[16:17], 0, v[134:135]
	s_mov_b32 m0, s54
	s_nop 0
	global_load_lds_dwordx4 v[226:227], off
	s_waitcnt vmcnt(8)
	s_waitcnt lgkmcnt(0)
	s_barrier
	s_setprio 1
	s_waitcnt lgkmcnt(0)
	v_mfma_f32_16x16x32_bf16 v[128:131], v[150:153], v[182:185], v[128:131]
	v_mfma_f32_16x16x32_bf16 v[124:127], v[158:161], v[182:185], v[124:127]
	v_mfma_f32_16x16x32_bf16 v[116:119], v[150:153], v[190:193], v[116:119]
	v_mfma_f32_16x16x32_bf16 v[112:115], v[158:161], v[190:193], v[112:115]
	v_mfma_f32_16x16x32_bf16 v[104:107], v[150:153], v[204:207], v[104:107]
	v_mfma_f32_16x16x32_bf16 v[96:99], v[158:161], v[204:207], v[96:99]
	v_mfma_f32_16x16x32_bf16 v[88:91], v[150:153], v[212:215], v[88:91]
	v_mfma_f32_16x16x32_bf16 v[80:83], v[158:161], v[212:215], v[80:83]
	v_mfma_f32_16x16x32_bf16 v[128:131], v[154:157], v[186:189], v[128:131]
	v_mfma_f32_16x16x32_bf16 v[124:127], v[162:165], v[186:189], v[124:127]
	v_mfma_f32_16x16x32_bf16 v[116:119], v[154:157], v[200:203], v[116:119]
	v_mfma_f32_16x16x32_bf16 v[112:115], v[162:165], v[200:203], v[112:115]
	v_mfma_f32_16x16x32_bf16 v[104:107], v[154:157], v[208:211], v[104:107]
	v_mfma_f32_16x16x32_bf16 v[96:99], v[162:165], v[208:211], v[96:99]
	v_mfma_f32_16x16x32_bf16 v[88:91], v[154:157], v[216:219], v[88:91]
	v_mfma_f32_16x16x32_bf16 v[80:83], v[162:165], v[216:219], v[80:83]
	s_setprio 0
	s_setprio 1
	v_mfma_f32_16x16x32_bf16 v[120:123], v[166:169], v[182:185], v[120:123]
	v_mfma_f32_16x16x32_bf16 v[108:111], v[174:177], v[182:185], v[108:111]
	v_mfma_f32_16x16x32_bf16 v[100:103], v[166:169], v[190:193], v[100:103]
	v_mfma_f32_16x16x32_bf16 v[92:95], v[174:177], v[190:193], v[92:95]
	v_mfma_f32_16x16x32_bf16 v[84:87], v[166:169], v[204:207], v[84:87]
	v_mfma_f32_16x16x32_bf16 v[76:79], v[174:177], v[204:207], v[76:79]
	v_mfma_f32_16x16x32_bf16 v[72:75], v[166:169], v[212:215], v[72:75]
	v_mfma_f32_16x16x32_bf16 v[68:71], v[174:177], v[212:215], v[68:71]
	v_mfma_f32_16x16x32_bf16 v[120:123], v[170:173], v[186:189], v[120:123]
	v_mfma_f32_16x16x32_bf16 v[108:111], v[178:181], v[186:189], v[108:111]
	v_mfma_f32_16x16x32_bf16 v[100:103], v[170:173], v[200:203], v[100:103]
	v_mfma_f32_16x16x32_bf16 v[92:95], v[178:181], v[200:203], v[92:95]
	v_mfma_f32_16x16x32_bf16 v[84:87], v[170:173], v[208:211], v[84:87]
	v_mfma_f32_16x16x32_bf16 v[76:79], v[178:181], v[208:211], v[76:79]
	v_mfma_f32_16x16x32_bf16 v[72:75], v[170:173], v[216:219], v[72:75]
	v_mfma_f32_16x16x32_bf16 v[68:71], v[178:181], v[216:219], v[68:71]
	s_setprio 0
	s_barrier
; __device__ __forceinline__ unsigned cvt_pk_bf16(float lo, float hi) { unsigned r; asm volatile("v_cvt_pk_bf16_f32 %0, %1, %2" : "=v"(r) : "v"(lo), "v"(hi)); return r; }
; #define PG8_STAGE(bufoff, gbase, voff) do { _Pragma("unroll") for (int _i = 0; _i < 2; ++_i) \
;         __builtin_amdgcn_global_load_lds((const unsigned*)((const char*)(gbase) + (voff)[_i]), (LAS unsigned*)(lds + (bufoff) + ldsw + _i * 8192), 16, 0, 0); } while (0)
; #define PG8_WAIT_V(n) asm volatile("s_waitcnt vmcnt(" #n ")" ::: "memory")
; #define PG8_WAIT_L(n) asm volatile("s_waitcnt lgkmcnt(" #n ")" ::: "memory")
; #define PG8_BAR __builtin_amdgcn_s_barrier()
; #define PG8_SCHED __builtin_amdgcn_sched_barrier(0)
;     ...
;             PG8_WAIT_V(8); PG8_WAIT_L(0); PG8_BAR; PG8_MMA(0, 0, At, B0); PG8_MMA(0, 1, At, B1); PG8_BAR; PG8_SCHED;
;             PG8_LDA(At, 1, 1); PG8_STAGE(PG8_SB(1, 0), b3, voffB); PG8_STAGE(PG8_SB(1, 1), b3 + hstepB, voffB); PG8_STAGE(PG8_SA(1, 0), a3, s0);
;             PG8_WAIT_V(8); PG8_WAIT_L(0); PG8_BAR; PG8_MMA(1, 0, At, B0); PG8_MMA(1, 1, At, B1); PG8_BAR; PG8_SCHED;
;     __device__ __forceinline__ void operator()(EPI_SIG) const {
;         const int g = u.pn >> 2, ct = u.pn & 3;
; #pragma unroll
;         for (int ai = 0; ai < 2; ++ai)
; #pragma unroll
;             for (int m = 0; m < 4; ++m)
; #pragma unroll
;                 for (int bj = 0; bj < 2; ++bj) { const int pn = ct * 4 + bj * 2 + (wc >> 1), wave_m = wr * 4 + (wc & 1) * 2 + (fq >> 1);
; #pragma unroll
;                     for (int n = 0; n < 2; ++n) { const int lane_m = ((fq & 1) * 2 + n) * 16 + fr; const f32x4 v = acc[ai][bj][m][n];
;                         v2u w; w.x = cvt_pk_bf16(v[0], v[1]); w.y = cvt_pk_bf16(v[2], v[3]);
;                         *(v2u*)(P2 + ((((((size_t)u.pm * 16 + pn) * 2 + ai) * 4 + m) * 8 + wave_m) * 4 + g) * 256 + lane_m * 4) = w; } }
	s_mov_b32 m0, s33
	v_lshl_add_u64 v[194:195], v[194:195], 0, s[96:97]
	ds_read_b128 v[182:185], v149 offset:49152
	ds_read_b128 v[186:189], v149 offset:50176
	ds_read_b128 v[190:193], v149 offset:51200
	ds_read_b128 v[200:203], v149 offset:52224
	ds_read_b128 v[204:207], v149 offset:53248
	ds_read_b128 v[208:211], v149 offset:54272
	ds_read_b128 v[212:215], v149 offset:55296
	ds_read_b128 v[216:219], v149 offset:56320
	global_load_lds_dwordx4 v[194:195], off
	v_lshl_add_u64 v[194:195], v[220:221], 0, s[96:97]
	s_mov_b32 m0, s11
	s_nop 0
	global_load_lds_dwordx4 v[194:195], off
	v_lshl_add_u64 v[194:195], s[14:15], 0, v[136:137]
	s_mov_b32 m0, s68
	s_nop 0
	global_load_lds_dwordx4 v[194:195], off
	v_lshl_add_u64 v[194:195], s[14:15], 0, v[132:133]
	s_mov_b32 m0, s67
	s_nop 0
	global_load_lds_dwordx4 v[194:195], off
	v_lshl_add_u64 v[194:195], v[222:223], 0, s[96:97]
	s_mov_b32 m0, s55
	s_nop 0
	global_load_lds_dwordx4 v[194:195], off
	v_lshl_add_u64 v[194:195], v[224:225], 0, s[96:97]
	s_mov_b32 m0, s56
	s_nop 0
	global_load_lds_dwordx4 v[194:195], off
	s_waitcnt vmcnt(8)
	s_waitcnt lgkmcnt(0)
	s_barrier
	s_setprio 1
	s_waitcnt lgkmcnt(0)
	v_mfma_f32_16x16x32_bf16 v[64:67], v[150:153], v[182:185], v[64:67]
	v_mfma_f32_16x16x32_bf16 v[60:63], v[158:161], v[182:185], v[60:63]
	v_mfma_f32_16x16x32_bf16 v[46:49], v[150:153], v[190:193], v[46:49]
	v_mfma_f32_16x16x32_bf16 v[38:41], v[158:161], v[190:193], v[38:41]
	v_mfma_f32_16x16x32_bf16 v[22:25], v[150:153], v[204:207], v[22:25]
	v_mfma_f32_16x16x32_bf16 v[14:17], v[158:161], v[204:207], v[14:17]
	v_mfma_f32_16x16x32_bf16 v[6:9], v[150:153], v[212:215], v[6:9]
	v_mfma_f32_16x16x32_bf16 v[2:5], v[158:161], v[212:215], v[2:5]
	v_mfma_f32_16x16x32_bf16 v[64:67], v[154:157], v[186:189], v[64:67]
	v_mfma_f32_16x16x32_bf16 v[60:63], v[162:165], v[186:189], v[60:63]
	v_mfma_f32_16x16x32_bf16 v[46:49], v[154:157], v[200:203], v[46:49]
	v_mfma_f32_16x16x32_bf16 v[38:41], v[162:165], v[200:203], v[38:41]
	v_mfma_f32_16x16x32_bf16 v[22:25], v[154:157], v[208:211], v[22:25]
	v_mfma_f32_16x16x32_bf16 v[14:17], v[162:165], v[208:211], v[14:17]
	v_mfma_f32_16x16x32_bf16 v[6:9], v[154:157], v[216:219], v[6:9]
	v_mfma_f32_16x16x32_bf16 v[2:5], v[162:165], v[216:219], v[2:5]
	s_setprio 0
	s_setprio 1
	v_mfma_f32_16x16x32_bf16 v[52:55], v[166:169], v[182:185], v[52:55]
	v_mfma_f32_16x16x32_bf16 v[34:37], v[174:177], v[182:185], v[34:37]
	v_mfma_f32_16x16x32_bf16 v[18:21], v[166:169], v[190:193], v[18:21]
	v_mfma_f32_16x16x32_bf16 v[10:13], v[174:177], v[190:193], v[10:13]
	v_mfma_f32_16x16x32_bf16 v[56:59], v[166:169], v[204:207], v[56:59]
	v_mfma_f32_16x16x32_bf16 v[42:45], v[174:177], v[204:207], v[42:45]
	v_mfma_f32_16x16x32_bf16 v[30:33], v[166:169], v[212:215], v[30:33]
	v_mfma_f32_16x16x32_bf16 v[26:29], v[174:177], v[212:215], v[26:29]
	v_mfma_f32_16x16x32_bf16 v[52:55], v[170:173], v[186:189], v[52:55]
	v_mfma_f32_16x16x32_bf16 v[34:37], v[178:181], v[186:189], v[34:37]
	v_mfma_f32_16x16x32_bf16 v[18:21], v[170:173], v[200:203], v[18:21]
	v_mfma_f32_16x16x32_bf16 v[10:13], v[178:181], v[200:203], v[10:13]
	v_mfma_f32_16x16x32_bf16 v[56:59], v[170:173], v[208:211], v[56:59]
	v_mfma_f32_16x16x32_bf16 v[42:45], v[178:181], v[208:211], v[42:45]
	v_mfma_f32_16x16x32_bf16 v[30:33], v[170:173], v[216:219], v[30:33]
	v_mfma_f32_16x16x32_bf16 v[26:29], v[178:181], v[216:219], v[26:29]
	s_setprio 0
	s_barrier
	s_andn2_b64 vcc, exec, s[2:3]
	s_mov_b64 s[14:15], -1
	s_mov_b64 s[2:3], 0
	s_mov_b64 s[16:17], 0x100
	s_cbranch_vccz .LBB0_1783
	s_and_b64 vcc, exec, s[8:9]
	s_cbranch_vccz .LBB0_1786
	s_barrier
.LBB0_1786:
	s_lshl_b32 s3, s61, 3
	s_and_b32 s3, s3, 24
	s_or_b32 s11, s3, s57
	s_ashr_i32 s41, s40, 31
	s_lshl_b64 s[14:15], s[40:41], 10
	s_lshl_b32 s11, s11, 5
	s_or_b32 s14, s11, s14
	s_ashr_i32 s2, s61, 2
	v_cvt_pk_bf16_f32 v128, v128, v129
	v_cvt_pk_bf16_f32 v129, v130, v131
	v_lshl_add_u64 v[130:131], s[14:15], 0, v[140:141]
	s_ashr_i32 s3, s2, 31
	v_lshlrev_b64 v[130:131], 11, v[130:131]
	s_lshl_b64 s[2:3], s[2:3], 9
	v_lshl_add_u64 v[130:131], s[6:7], 0, v[130:131]
	v_lshl_add_u64 v[130:131], v[130:131], 0, s[2:3]
	v_lshl_add_u64 v[130:131], v[130:131], 0, v[50:51]
	s_or_b32 s16, s14, 0x80
	s_mov_b32 s17, s15
	flat_store_dwordx2 v[130:131], v[128:129] nt
	v_cvt_pk_bf16_f32 v124, v124, v125
	v_cvt_pk_bf16_f32 v125, v126, v127
	flat_store_dwordx2 v[130:131], v[124:125] offset:128 nt
	v_cvt_pk_bf16_f32 v120, v120, v121
	v_cvt_pk_bf16_f32 v121, v122, v123
	v_lshl_add_u64 v[122:123], s[16:17], 0, v[140:141]
	v_lshlrev_b64 v[122:123], 11, v[122:123]
	v_lshl_add_u64 v[122:123], s[6:7], 0, v[122:123]
	v_lshl_add_u64 v[122:123], v[122:123], 0, s[2:3]
	v_lshl_add_u64 v[122:123], v[122:123], 0, v[50:51]
	flat_store_dwordx2 v[122:123], v[120:121] nt
	v_cvt_pk_bf16_f32 v108, v108, v109
	v_cvt_pk_bf16_f32 v109, v110, v111
	v_lshl_add_u64 v[110:111], s[14:15], 0, v[142:143]
	v_lshlrev_b64 v[110:111], 11, v[110:111]
	v_lshl_add_u64 v[110:111], s[6:7], 0, v[110:111]
	v_lshl_add_u64 v[110:111], v[110:111], 0, s[2:3]
	flat_store_dwordx2 v[122:123], v[108:109] offset:128 nt
	v_cvt_pk_bf16_f32 v108, v116, v117
	v_cvt_pk_bf16_f32 v109, v118, v119
	v_lshl_add_u64 v[110:111], v[110:111], 0, v[50:51]
	flat_store_dwordx2 v[110:111], v[108:109] nt
	v_cvt_pk_bf16_f32 v108, v112, v113
	v_cvt_pk_bf16_f32 v109, v114, v115
	flat_store_dwordx2 v[110:111], v[108:109] offset:128 nt
	v_cvt_pk_bf16_f32 v100, v100, v101
	v_cvt_pk_bf16_f32 v101, v102, v103
	v_lshl_add_u64 v[102:103], s[16:17], 0, v[142:143]
	v_lshlrev_b64 v[102:103], 11, v[102:103]
	v_lshl_add_u64 v[102:103], s[6:7], 0, v[102:103]
	v_lshl_add_u64 v[102:103], v[102:103], 0, s[2:3]
; __device__ __forceinline__ unsigned cvt_pk_bf16(float lo, float hi) { unsigned r; asm volatile("v_cvt_pk_bf16_f32 %0, %1, %2" : "=v"(r) : "v"(lo), "v"(hi)); return r; }
;     __device__ __forceinline__ void operator()(EPI_SIG) const {
;         const int g = u.pn >> 2, ct = u.pn & 3;
; #pragma unroll
;         for (int ai = 0; ai < 2; ++ai)
; #pragma unroll
;             for (int m = 0; m < 4; ++m)
; #pragma unroll
;                 for (int bj = 0; bj < 2; ++bj) { const int pn = ct * 4 + bj * 2 + (wc >> 1), wave_m = wr * 4 + (wc & 1) * 2 + (fq >> 1);
; #pragma unroll
;                     for (int n = 0; n < 2; ++n) { const int lane_m = ((fq & 1) * 2 + n) * 16 + fr; const f32x4 v = acc[ai][bj][m][n];
;                         v2u w; w.x = cvt_pk_bf16(v[0], v[1]); w.y = cvt_pk_bf16(v[2], v[3]);
;                         *(v2u*)(P2 + ((((((size_t)u.pm * 16 + pn) * 2 + ai) * 4 + m) * 8 + wave_m) * 4 + g) * 256 + lane_m * 4) = w; } }
	v_lshl_add_u64 v[102:103], v[102:103], 0, v[50:51]
	flat_store_dwordx2 v[102:103], v[100:101] nt
	v_cvt_pk_bf16_f32 v92, v92, v93
	v_cvt_pk_bf16_f32 v93, v94, v95
	v_lshl_add_u64 v[94:95], s[14:15], 0, v[144:145]
	v_lshlrev_b64 v[94:95], 11, v[94:95]
	v_lshl_add_u64 v[94:95], s[6:7], 0, v[94:95]
	v_lshl_add_u64 v[94:95], v[94:95], 0, s[2:3]
	flat_store_dwordx2 v[102:103], v[92:93] offset:128 nt
	v_cvt_pk_bf16_f32 v92, v104, v105
	v_cvt_pk_bf16_f32 v93, v106, v107
	v_lshl_add_u64 v[94:95], v[94:95], 0, v[50:51]
	flat_store_dwordx2 v[94:95], v[92:93] nt
	v_cvt_pk_bf16_f32 v92, v96, v97
	v_cvt_pk_bf16_f32 v93, v98, v99
	flat_store_dwordx2 v[94:95], v[92:93] offset:128 nt
	v_cvt_pk_bf16_f32 v84, v84, v85
	v_cvt_pk_bf16_f32 v85, v86, v87
	v_lshl_add_u64 v[86:87], s[16:17], 0, v[144:145]
	v_lshlrev_b64 v[86:87], 11, v[86:87]
	v_lshl_add_u64 v[86:87], s[6:7], 0, v[86:87]
	v_lshl_add_u64 v[86:87], v[86:87], 0, s[2:3]
	v_lshl_add_u64 v[86:87], v[86:87], 0, v[50:51]
	flat_store_dwordx2 v[86:87], v[84:85] nt
	v_cvt_pk_bf16_f32 v76, v76, v77
	v_cvt_pk_bf16_f32 v77, v78, v79
	v_lshl_add_u64 v[78:79], s[14:15], 0, v[146:147]
	v_lshlrev_b64 v[78:79], 11, v[78:79]
	v_lshl_add_u64 v[78:79], s[6:7], 0, v[78:79]
	v_lshl_add_u64 v[78:79], v[78:79], 0, s[2:3]
	flat_store_dwordx2 v[86:87], v[76:77] offset:128 nt
	v_cvt_pk_bf16_f32 v76, v88, v89
	v_cvt_pk_bf16_f32 v77, v90, v91
	v_lshl_add_u64 v[78:79], v[78:79], 0, v[50:51]
	flat_store_dwordx2 v[78:79], v[76:77] nt
	v_cvt_pk_bf16_f32 v76, v80, v81
	v_cvt_pk_bf16_f32 v77, v82, v83
	flat_store_dwordx2 v[78:79], v[76:77] offset:128 nt
	v_cvt_pk_bf16_f32 v72, v72, v73
	v_cvt_pk_bf16_f32 v73, v74, v75
	v_lshl_add_u64 v[74:75], s[16:17], 0, v[146:147]
	v_lshlrev_b64 v[74:75], 11, v[74:75]
	v_lshl_add_u64 v[74:75], s[6:7], 0, v[74:75]
	v_lshl_add_u64 v[74:75], v[74:75], 0, s[2:3]
	v_lshl_add_u64 v[74:75], v[74:75], 0, v[50:51]
	s_or_b32 s16, s14, 32
	flat_store_dwordx2 v[74:75], v[72:73] nt
	v_cvt_pk_bf16_f32 v68, v68, v69
	v_cvt_pk_bf16_f32 v69, v70, v71
	flat_store_dwordx2 v[74:75], v[68:69] offset:128 nt
	v_cvt_pk_bf16_f32 v64, v64, v65
	v_cvt_pk_bf16_f32 v65, v66, v67
	v_lshl_add_u64 v[66:67], s[16:17], 0, v[140:141]
	v_lshlrev_b64 v[66:67], 11, v[66:67]
	v_lshl_add_u64 v[66:67], s[6:7], 0, v[66:67]
	v_lshl_add_u64 v[66:67], v[66:67], 0, s[2:3]
	v_lshl_add_u64 v[66:67], v[66:67], 0, v[50:51]
	s_or_b32 s14, s14, 0xa0
	flat_store_dwordx2 v[66:67], v[64:65] nt
	v_cvt_pk_bf16_f32 v60, v60, v61
	v_cvt_pk_bf16_f32 v61, v62, v63
	flat_store_dwordx2 v[66:67], v[60:61] offset:128 nt
	v_cvt_pk_bf16_f32 v52, v52, v53
	v_cvt_pk_bf16_f32 v53, v54, v55
	v_lshl_add_u64 v[54:55], s[14:15], 0, v[140:141]
	v_lshlrev_b64 v[54:55], 11, v[54:55]
	v_lshl_add_u64 v[54:55], s[6:7], 0, v[54:55]
	v_lshl_add_u64 v[54:55], v[54:55], 0, s[2:3]
	v_lshl_add_u64 v[54:55], v[54:55], 0, v[50:51]
	flat_store_dwordx2 v[54:55], v[52:53] nt
	v_cvt_pk_bf16_f32 v34, v34, v35
	v_cvt_pk_bf16_f32 v35, v36, v37
	v_lshl_add_u64 v[36:37], s[16:17], 0, v[142:143]
	v_lshlrev_b64 v[36:37], 11, v[36:37]
	v_lshl_add_u64 v[36:37], s[6:7], 0, v[36:37]
	v_lshl_add_u64 v[36:37], v[36:37], 0, s[2:3]
	flat_store_dwordx2 v[54:55], v[34:35] offset:128 nt
	v_cvt_pk_bf16_f32 v34, v46, v47
	v_cvt_pk_bf16_f32 v35, v48, v49
	v_lshl_add_u64 v[36:37], v[36:37], 0, v[50:51]
	flat_store_dwordx2 v[36:37], v[34:35] nt
	v_cvt_pk_bf16_f32 v34, v38, v39
	v_cvt_pk_bf16_f32 v35, v40, v41
	flat_store_dwordx2 v[36:37], v[34:35] offset:128 nt
	v_cvt_pk_bf16_f32 v18, v18, v19
	v_cvt_pk_bf16_f32 v19, v20, v21
	v_lshl_add_u64 v[20:21], s[14:15], 0, v[142:143]
	v_lshlrev_b64 v[20:21], 11, v[20:21]
	v_lshl_add_u64 v[20:21], s[6:7], 0, v[20:21]
	v_lshl_add_u64 v[20:21], v[20:21], 0, s[2:3]
	v_lshl_add_u64 v[20:21], v[20:21], 0, v[50:51]
	flat_store_dwordx2 v[20:21], v[18:19] nt
	v_cvt_pk_bf16_f32 v10, v10, v11
	v_cvt_pk_bf16_f32 v11, v12, v13
	v_lshl_add_u64 v[12:13], s[16:17], 0, v[144:145]
	v_lshlrev_b64 v[12:13], 11, v[12:13]
	v_lshl_add_u64 v[12:13], s[6:7], 0, v[12:13]
	v_lshl_add_u64 v[12:13], v[12:13], 0, s[2:3]
	flat_store_dwordx2 v[20:21], v[10:11] offset:128 nt
	v_cvt_pk_bf16_f32 v10, v22, v23
	v_cvt_pk_bf16_f32 v11, v24, v25
	v_lshl_add_u64 v[12:13], v[12:13], 0, v[50:51]
	flat_store_dwordx2 v[12:13], v[10:11] nt
	v_cvt_pk_bf16_f32 v10, v14, v15
	v_cvt_pk_bf16_f32 v11, v16, v17
	flat_store_dwordx2 v[12:13], v[10:11] offset:128 nt
	v_lshl_add_u64 v[12:13], s[14:15], 0, v[144:145]
	v_lshlrev_b64 v[12:13], 11, v[12:13]
	v_lshl_add_u64 v[12:13], s[6:7], 0, v[12:13]
	v_lshl_add_u64 v[12:13], v[12:13], 0, s[2:3]
	v_cvt_pk_bf16_f32 v10, v56, v57
	v_cvt_pk_bf16_f32 v11, v58, v59
	v_lshl_add_u64 v[12:13], v[12:13], 0, v[50:51]
	flat_store_dwordx2 v[12:13], v[10:11] nt
	v_cvt_pk_bf16_f32 v10, v42, v43
	v_cvt_pk_bf16_f32 v11, v44, v45
	flat_store_dwordx2 v[12:13], v[10:11] offset:128 nt
	v_cvt_pk_bf16_f32 v6, v6, v7
	v_cvt_pk_bf16_f32 v7, v8, v9
	v_lshl_add_u64 v[8:9], s[16:17], 0, v[146:147]
	v_lshlrev_b64 v[8:9], 11, v[8:9]
	v_lshl_add_u64 v[8:9], s[6:7], 0, v[8:9]
	v_lshl_add_u64 v[8:9], v[8:9], 0, s[2:3]
	v_lshl_add_u64 v[8:9], v[8:9], 0, v[50:51]
	flat_store_dwordx2 v[8:9], v[6:7] nt
	v_cvt_pk_bf16_f32 v2, v2, v3
	v_cvt_pk_bf16_f32 v3, v4, v5
	v_lshl_add_u64 v[4:5], s[14:15], 0, v[146:147]
	v_lshlrev_b64 v[4:5], 11, v[4:5]
	v_lshl_add_u64 v[4:5], s[6:7], 0, v[4:5]
	v_lshl_add_u64 v[4:5], v[4:5], 0, s[2:3]
	v_readlane_b32 s34, v255, 0
	s_mov_b32 s30, 0x3f3504f3
	flat_store_dwordx2 v[8:9], v[2:3] offset:128 nt
	v_cvt_pk_bf16_f32 v2, v30, v31
	v_cvt_pk_bf16_f32 v3, v32, v33
	v_lshl_add_u64 v[4:5], v[4:5], 0, v[50:51]
	s_andn2_b64 vcc, exec, s[0:1]
	s_mov_b64 s[0:1], -1
	v_readlane_b32 s35, v255, 1
	s_mov_b32 s31, 0xbf3504f3
	s_movk_i32 s68, 0x2200
	v_readlane_b32 s62, v255, 4
	s_mov_b32 s63, 0xbf6c835e
	s_movk_i32 s64, 0x440
	flat_store_dwordx2 v[4:5], v[2:3] nt
	v_cvt_pk_bf16_f32 v2, v26, v27
	v_cvt_pk_bf16_f32 v3, v28, v29
	flat_store_dwordx2 v[4:5], v[2:3] offset:128 nt
	s_mov_b32 s32, 1
	s_cbranch_vccnz .LBB0_1779
	s_andn2_b64 vcc, exec, s[4:5]
	s_cbranch_vccnz .LBB0_1778
	s_barrier
	s_branch .LBB0_1778
